# PV blocks of the MLA, SB and FoX tile loops: counted lgkmcnt before each MFMA instead of lgkmcnt(0) per 4-MFMA group (V fragment reads get three MFMA times to land)
# baseline (speedup 1.0000x reference)
.LBB0_930:
	v_cvt_pk_bf16_f32 v2, v2, v3
	v_cvt_pk_bf16_f32 v3, v4, v5
	v_cvt_pk_bf16_f32 v4, v112, v113
	v_cvt_pk_bf16_f32 v5, v114, v115
	v_cvt_pk_bf16_f32 v102, v102, v103
	v_cvt_pk_bf16_f32 v103, v104, v105
	v_cvt_pk_bf16_f32 v104, v106, v107
	v_cvt_pk_bf16_f32 v105, v108, v109
	v_cvt_pk_bf16_f32 v6, v6, v7
	v_cvt_pk_bf16_f32 v7, v8, v9
	v_cvt_pk_bf16_f32 v8, v10, v11
	v_cvt_pk_bf16_f32 v9, v13, v15
	v_cvt_pk_bf16_f32 v10, v12, v14
	v_cvt_pk_bf16_f32 v11, v96, v97
	v_cvt_pk_bf16_f32 v12, v98, v99
	v_cvt_pk_bf16_f32 v13, v100, v101
	v_fma_f32 v189, v189, v0, v110
	v_add_u32_e32 v0, s2, v214
	ds_read_b64_tr_b16 v[96:97], v0 offset:0x0
	ds_read_b64_tr_b16 v[98:99], v0 offset:0x100
	ds_read_b64_tr_b16 v[106:107], v0 offset:0x1000
	ds_read_b64_tr_b16 v[108:109], v0 offset:0x1100
	ds_read_b64_tr_b16 v[110:111], v0 offset:0x2000
	ds_read_b64_tr_b16 v[112:113], v0 offset:0x2100
	ds_read_b64_tr_b16 v[114:115], v0 offset:0x3000
	ds_read_b64_tr_b16 v[116:117], v0 offset:0x3100
	s_waitcnt lgkmcnt(6)
	s_nop 0
	v_mfma_f32_32x32x16_bf16 v[64:79], v[2:5], v[96:99], v[64:79]
	ds_read_b64_tr_b16 v[96:97], v0 offset:0x200
	ds_read_b64_tr_b16 v[98:99], v0 offset:0x300
	s_waitcnt lgkmcnt(6)
	v_mfma_f32_32x32x16_bf16 v[64:79], v[102:105], v[106:109], v[64:79]
	ds_read_b64_tr_b16 v[106:107], v0 offset:0x1200
	ds_read_b64_tr_b16 v[108:109], v0 offset:0x1300
	s_waitcnt lgkmcnt(6)
	v_mfma_f32_32x32x16_bf16 v[64:79], v[6:9], v[110:113], v[64:79]
	ds_read_b64_tr_b16 v[110:111], v0 offset:0x2200
	ds_read_b64_tr_b16 v[112:113], v0 offset:0x2300
	s_waitcnt lgkmcnt(6)
	v_mfma_f32_32x32x16_bf16 v[64:79], v[10:13], v[114:117], v[64:79]
	ds_read_b64_tr_b16 v[114:115], v0 offset:0x3200
	ds_read_b64_tr_b16 v[116:117], v0 offset:0x3300
	s_waitcnt lgkmcnt(6)
	v_mfma_f32_32x32x16_bf16 v[48:63], v[2:5], v[96:99], v[48:63]
	ds_read_b64_tr_b16 v[96:97], v0 offset:0x400
	ds_read_b64_tr_b16 v[98:99], v0 offset:0x500
	s_waitcnt lgkmcnt(6)
	v_mfma_f32_32x32x16_bf16 v[48:63], v[102:105], v[106:109], v[48:63]
	ds_read_b64_tr_b16 v[106:107], v0 offset:0x1400
	ds_read_b64_tr_b16 v[108:109], v0 offset:0x1500
	s_waitcnt lgkmcnt(6)
	v_mfma_f32_32x32x16_bf16 v[48:63], v[6:9], v[110:113], v[48:63]
	ds_read_b64_tr_b16 v[110:111], v0 offset:0x2400
	ds_read_b64_tr_b16 v[112:113], v0 offset:0x2500
	s_waitcnt lgkmcnt(6)
	v_mfma_f32_32x32x16_bf16 v[48:63], v[10:13], v[114:117], v[48:63]
	ds_read_b64_tr_b16 v[114:115], v0 offset:0x3400
	ds_read_b64_tr_b16 v[116:117], v0 offset:0x3500
	s_waitcnt lgkmcnt(6)
	v_mfma_f32_32x32x16_bf16 v[32:47], v[2:5], v[96:99], v[32:47]
	ds_read_b64_tr_b16 v[96:97], v0 offset:0x600
	ds_read_b64_tr_b16 v[98:99], v0 offset:0x700
	s_waitcnt lgkmcnt(6)
	v_mfma_f32_32x32x16_bf16 v[32:47], v[102:105], v[106:109], v[32:47]
	ds_read_b64_tr_b16 v[106:107], v0 offset:0x1600
	ds_read_b64_tr_b16 v[108:109], v0 offset:0x1700
	s_waitcnt lgkmcnt(6)
	v_mfma_f32_32x32x16_bf16 v[32:47], v[6:9], v[110:113], v[32:47]
	ds_read_b64_tr_b16 v[110:111], v0 offset:0x2600
	ds_read_b64_tr_b16 v[112:113], v0 offset:0x2700
	s_waitcnt lgkmcnt(6)
	v_mfma_f32_32x32x16_bf16 v[32:47], v[10:13], v[114:117], v[32:47]
	ds_read_b64_tr_b16 v[114:115], v0 offset:0x3600
	ds_read_b64_tr_b16 v[116:117], v0 offset:0x3700
	s_waitcnt lgkmcnt(6)
	v_mfma_f32_32x32x16_bf16 v[16:31], v[2:5], v[96:99], v[16:31]
	s_waitcnt lgkmcnt(4)
	v_mfma_f32_32x32x16_bf16 v[16:31], v[102:105], v[106:109], v[16:31]
	s_waitcnt lgkmcnt(2)
	v_mfma_f32_32x32x16_bf16 v[16:31], v[6:9], v[110:113], v[16:31]
	s_waitcnt lgkmcnt(0)
	v_mfma_f32_32x32x16_bf16 v[16:31], v[10:13], v[114:117], v[16:31]
	s_and_b64 vcc, exec, s[94:95]
	s_cbranch_vccnz .Lmla_w0
	s_waitcnt vmcnt(5)
	s_cmp_ge_i32 s96, s26
	s_barrier
	s_cbranch_scc0 .LBB0_914
	s_branch .Lmla_exit

.LBB0_1107:
	s_add_i32 s0, s20, 0x80
	s_cmp_ge_i32 s0, s36
	s_cselect_b64 s[0:1], -1, 0
	s_or_b64 s[0:1], s[0:1], s[18:19]
	s_and_b64 vcc, exec, s[0:1]
	s_cbranch_vccnz .LBB0_1109
	s_add_i32 s0, s20, 0xbf
	s_cmp_lt_i32 s0, s27
	s_mul_i32 s0, s93, 0xa100
	s_mov_b32 s35, s36
	s_mov_b32 s36, s27
	s_cselect_b64 s[26:27], -1, 0
	s_add_i32 s0, s0, 0
	v_add_u32_e32 v0, s0, v160
	ds_read_b128 v[2:5], v0
	ds_read_b128 v[6:9], v0 offset:8192
	v_add_u32_e32 v0, s0, v161
	ds_read_b128 v[10:13], v0
	ds_read_b128 v[170:173], v0 offset:8192
	s_setprio 1
	v_add_u32_e32 v0, s0, v162
	ds_read_b128 v[174:177], v0
	ds_read_b128 v[178:181], v0 offset:8192
	v_add_u32_e32 v0, s0, v163
	ds_read_b128 v[182:185], v0
	ds_read_b128 v[186:189], v0 offset:8192
	s_waitcnt lgkmcnt(7)
	v_mfma_f32_32x32x16_bf16 v[96:111], v[2:5], v[112:115], 0
	s_waitcnt lgkmcnt(6)
	v_mfma_f32_32x32x16_bf16 v[80:95], v[6:9], v[112:115], 0
	s_waitcnt lgkmcnt(5)
	v_mfma_f32_32x32x16_bf16 v[96:111], v[10:13], v[116:119], v[96:111]
	s_waitcnt lgkmcnt(4)
	v_mfma_f32_32x32x16_bf16 v[80:95], v[170:173], v[116:119], v[80:95]
	v_add_u32_e32 v0, s0, v165
	ds_read_b128 v[2:5], v0 offset:8192
	ds_read_b128 v[6:9], v0
	v_add_u32_e32 v0, s0, v166
	ds_read_b128 v[10:13], v0 offset:8192
	ds_read_b128 v[170:173], v0
	s_waitcnt lgkmcnt(7)
	v_mfma_f32_32x32x16_bf16 v[96:111], v[174:177], v[120:123], v[96:111]
	s_waitcnt lgkmcnt(6)
	v_mfma_f32_32x32x16_bf16 v[80:95], v[178:181], v[120:123], v[80:95]
	s_waitcnt lgkmcnt(5)
	v_mfma_f32_32x32x16_bf16 v[96:111], v[182:185], v[124:127], v[96:111]
	s_waitcnt lgkmcnt(4)
	v_mfma_f32_32x32x16_bf16 v[80:95], v[186:189], v[124:127], v[80:95]
	v_add_u32_e32 v0, s0, v167
	ds_read_b128 v[174:177], v0
	ds_read_b128 v[178:181], v0 offset:8192
	v_add_u32_e32 v0, s0, v168
	ds_read_b128 v[182:185], v0
	ds_read_b128 v[186:189], v0 offset:8192
	s_waitcnt lgkmcnt(4)
	v_mfma_f32_32x32x16_bf16 v[96:111], v[170:173], v[128:131], v[96:111]
	v_mfma_f32_32x32x16_bf16 v[80:95], v[10:13], v[128:131], v[80:95]
	v_mfma_f32_32x32x16_bf16 v[96:111], v[6:9], v[132:135], v[96:111]
	v_mfma_f32_32x32x16_bf16 v[80:95], v[2:5], v[132:135], v[80:95]
	s_waitcnt lgkmcnt(3)
	v_mfma_f32_32x32x16_bf16 v[96:111], v[174:177], v[136:139], v[96:111]
	s_waitcnt lgkmcnt(2)
	v_mfma_f32_32x32x16_bf16 v[80:95], v[178:181], v[136:139], v[80:95]
	s_waitcnt lgkmcnt(1)
	v_mfma_f32_32x32x16_bf16 v[96:111], v[182:185], v[140:143], v[96:111]
	s_waitcnt lgkmcnt(0)
	v_mfma_f32_32x32x16_bf16 v[80:95], v[186:189], v[140:143], v[80:95]
	s_setprio 0
	v_add_u32_e32 v8, s20, v158
	v_add_u32_e32 v0, 0x80, v8
	v_cmp_lt_i32_e32 vcc, v0, v164
	v_add_u32_e32 v0, 0xa0, v8
	s_mov_b32 s3, 0xbfb8aa3b
	v_cmp_lt_i32_e64 s[0:1], v0, v164
	s_nop 2
	v_mul_f32_e64 v0, |v96|, s3
	v_exp_f32_e32 v0, v0
	v_max_f32_e32 v2, v96, v96
	v_max_f32_e32 v2, 0, v2
	v_mul_f32_e64 v3, |v80|, s3
	v_add_f32_e32 v0, 1.0, v0
	v_log_f32_e32 v0, v0
	s_or_b64 vcc, s[26:27], vcc
	v_exp_f32_e32 v3, v3
	s_mov_b32 s2, s7
	v_fmac_f32_e32 v2, 0x3f317218, v0
	v_max_f32_e32 v0, v80, v80
	v_max_f32_e32 v4, 0, v0
	v_cndmask_b32_e64 v0, 0, -v2, vcc
	v_add_u32_e32 v2, 0x81, v8
	v_cmp_lt_i32_e64 s[4:5], v2, v164
	v_add_u32_e32 v2, 0xa1, v8
	v_cmp_lt_i32_e64 s[6:7], v2, v164
	v_mul_f32_e64 v2, |v97|, s3
	v_exp_f32_e32 v2, v2
	v_add_f32_e32 v3, 1.0, v3
	v_log_f32_e32 v3, v3
	s_or_b64 s[0:1], s[26:27], s[0:1]
	v_add_f32_e32 v2, 1.0, v2
	v_log_f32_e32 v2, v2
	v_fmac_f32_e32 v4, 0x3f317218, v3
	v_cndmask_b32_e64 v3, 0, -v4, s[0:1]
	v_max_f32_e32 v4, v97, v97
	v_max_f32_e32 v4, 0, v4
	v_mul_f32_e64 v5, |v81|, s3
	v_fmac_f32_e32 v4, 0x3f317218, v2
	v_max_f32_e32 v2, v81, v81
	s_or_b64 s[14:15], s[26:27], s[4:5]
	v_exp_f32_e32 v5, v5
	v_max_f32_e32 v6, 0, v2
	v_cndmask_b32_e64 v2, 0, -v4, s[14:15]
	v_add_u32_e32 v4, 0x82, v8
	s_or_b64 s[4:5], s[26:27], s[6:7]
	v_cmp_lt_i32_e64 s[6:7], v4, v164
	v_add_u32_e32 v4, 0xa2, v8
	v_cmp_lt_i32_e64 s[8:9], v4, v164
	v_mul_f32_e64 v4, |v98|, s3
	v_exp_f32_e32 v4, v4
	v_add_f32_e32 v5, 1.0, v5
	v_log_f32_e32 v5, v5
	v_mul_f32_e64 v7, |v82|, s3
	v_add_f32_e32 v4, 1.0, v4
	v_log_f32_e32 v4, v4
	v_fmac_f32_e32 v6, 0x3f317218, v5
	v_cndmask_b32_e64 v5, 0, -v6, s[4:5]
	v_max_f32_e32 v6, v98, v98
	v_max_f32_e32 v6, 0, v6
	v_fmac_f32_e32 v6, 0x3f317218, v4
	v_max_f32_e32 v4, v82, v82
	s_or_b64 s[6:7], s[26:27], s[6:7]
	v_exp_f32_e32 v7, v7
	v_max_f32_e32 v9, 0, v4
	v_cndmask_b32_e64 v4, 0, -v6, s[6:7]
	v_add_u32_e32 v6, 0x83, v8
	v_cmp_lt_i32_e64 s[10:11], v6, v164
	v_add_u32_e32 v6, 0xa3, v8
	v_cmp_lt_i32_e64 s[12:13], v6, v164
	v_mul_f32_e64 v6, |v99|, s3
	v_exp_f32_e32 v6, v6
	v_add_f32_e32 v7, 1.0, v7
	v_log_f32_e32 v7, v7
	v_mul_f32_e64 v10, |v83|, s3
	v_exp_f32_e32 v10, v10
	v_add_f32_e32 v6, 1.0, v6
	v_log_f32_e32 v6, v6
	v_fmac_f32_e32 v9, 0x3f317218, v7
	s_or_b64 s[8:9], s[26:27], s[8:9]
	v_cndmask_b32_e64 v7, 0, -v9, s[8:9]
	v_max_f32_e32 v9, v99, v99
	v_max_f32_e32 v9, 0, v9
	v_add_f32_e32 v10, 1.0, v10
	v_log_f32_e32 v10, v10
	v_fmac_f32_e32 v9, 0x3f317218, v6
	v_max_f32_e32 v6, v83, v83
	s_or_b64 s[10:11], s[26:27], s[10:11]
	v_max_f32_e32 v11, 0, v6
	v_cndmask_b32_e64 v6, 0, -v9, s[10:11]
	v_add_u32_e32 v9, 0x88, v8
	v_cmp_lt_i32_e64 s[42:43], v9, v164
	v_add_u32_e32 v9, 0xa8, v8
	v_cmp_lt_i32_e64 s[44:45], v9, v164
	v_mul_f32_e64 v9, |v100|, s3
	v_fmac_f32_e32 v11, 0x3f317218, v10
	s_or_b64 s[12:13], s[26:27], s[12:13]
	v_exp_f32_e32 v9, v9
	v_cndmask_b32_e64 v15, 0, -v11, s[12:13]
	v_mul_f32_e64 v11, |v84|, s3
	v_exp_f32_e32 v11, v11
	v_add_f32_e32 v9, 1.0, v9
	v_log_f32_e32 v9, v9
	v_max_f32_e32 v10, v100, v100
	v_add_f32_e32 v11, 1.0, v11
	v_log_f32_e32 v11, v11
	v_max_f32_e32 v10, 0, v10
	v_fmac_f32_e32 v10, 0x3f317218, v9
	v_max_f32_e32 v9, v84, v84
	v_max_f32_e32 v9, 0, v9
	v_fmac_f32_e32 v9, 0x3f317218, v11
	s_or_b64 s[44:45], s[26:27], s[44:45]
	v_cndmask_b32_e64 v171, 0, -v9, s[44:45]
	v_add_u32_e32 v9, 0x89, v8
	v_cmp_lt_i32_e64 s[46:47], v9, v164
	v_add_u32_e32 v9, 0xa9, v8
	v_cmp_lt_i32_e64 s[48:49], v9, v164
	v_mul_f32_e64 v9, |v101|, s3
	v_exp_f32_e32 v9, v9
	v_mul_f32_e64 v11, |v85|, s3
	v_exp_f32_e32 v11, v11
	s_or_b64 s[42:43], s[26:27], s[42:43]
	v_add_f32_e32 v9, 1.0, v9
	v_log_f32_e32 v9, v9
	v_add_f32_e32 v11, 1.0, v11
	v_cndmask_b32_e64 v169, 0, -v10, s[42:43]
	v_max_f32_e32 v10, v101, v101
	v_log_f32_e32 v11, v11
	v_max_f32_e32 v10, 0, v10
	v_fmac_f32_e32 v10, 0x3f317218, v9
	v_max_f32_e32 v9, v85, v85
	v_max_f32_e32 v9, 0, v9
	v_fmac_f32_e32 v9, 0x3f317218, v11
	s_or_b64 s[48:49], s[26:27], s[48:49]
	v_cndmask_b32_e64 v173, 0, -v9, s[48:49]
	v_add_u32_e32 v9, 0x8a, v8
	v_cmp_lt_i32_e64 s[50:51], v9, v164
	v_add_u32_e32 v9, 0xaa, v8
	v_cmp_lt_i32_e64 s[52:53], v9, v164
	v_mul_f32_e64 v9, |v102|, s3
	v_exp_f32_e32 v9, v9
	v_mul_f32_e64 v11, |v86|, s3
	v_exp_f32_e32 v11, v11
	s_or_b64 s[46:47], s[26:27], s[46:47]
	v_add_f32_e32 v9, 1.0, v9
	v_log_f32_e32 v9, v9
	v_add_f32_e32 v11, 1.0, v11
	v_cndmask_b32_e64 v176, 0, -v10, s[46:47]
	v_max_f32_e32 v10, v102, v102
	v_log_f32_e32 v11, v11
	v_max_f32_e32 v10, 0, v10
	v_fmac_f32_e32 v10, 0x3f317218, v9
	v_max_f32_e32 v9, v86, v86
	v_max_f32_e32 v9, 0, v9
	v_fmac_f32_e32 v9, 0x3f317218, v11
	s_or_b64 s[52:53], s[26:27], s[52:53]
	v_cndmask_b32_e64 v178, 0, -v9, s[52:53]
	v_add_u32_e32 v9, 0x8b, v8
	v_cmp_lt_i32_e64 s[54:55], v9, v164
	v_add_u32_e32 v9, 0xab, v8
	v_cmp_lt_i32_e64 s[56:57], v9, v164
	v_mul_f32_e64 v9, |v103|, s3
	v_exp_f32_e32 v9, v9
	v_mul_f32_e64 v11, |v87|, s3
	v_exp_f32_e32 v11, v11
	s_or_b64 s[50:51], s[26:27], s[50:51]
	v_add_f32_e32 v9, 1.0, v9
	v_log_f32_e32 v9, v9
	v_add_f32_e32 v11, 1.0, v11
	v_cndmask_b32_e64 v177, 0, -v10, s[50:51]
	v_max_f32_e32 v10, v103, v103
	v_log_f32_e32 v11, v11
	v_max_f32_e32 v10, 0, v10
	v_fmac_f32_e32 v10, 0x3f317218, v9
	v_max_f32_e32 v9, v87, v87
	v_max_f32_e32 v9, 0, v9
	v_fmac_f32_e32 v9, 0x3f317218, v11
	s_or_b64 s[56:57], s[26:27], s[56:57]
	v_cndmask_b32_e64 v180, 0, -v9, s[56:57]
	v_add_u32_e32 v9, 0x90, v8
	v_cmp_lt_i32_e64 s[58:59], v9, v164
	v_add_u32_e32 v9, 0xb0, v8
	v_cmp_lt_i32_e64 s[60:61], v9, v164
	v_mul_f32_e64 v9, |v104|, s3
	v_exp_f32_e32 v9, v9
	v_mul_f32_e64 v11, |v88|, s3
	v_exp_f32_e32 v11, v11
	s_or_b64 s[54:55], s[26:27], s[54:55]
	v_add_f32_e32 v9, 1.0, v9
	v_log_f32_e32 v9, v9
	v_add_f32_e32 v11, 1.0, v11
	v_cndmask_b32_e64 v179, 0, -v10, s[54:55]
	v_max_f32_e32 v10, v104, v104
	v_log_f32_e32 v11, v11
	v_max_f32_e32 v10, 0, v10
	v_fmac_f32_e32 v10, 0x3f317218, v9
	v_max_f32_e32 v9, v88, v88
	v_max_f32_e32 v9, 0, v9
	v_fmac_f32_e32 v9, 0x3f317218, v11
	s_or_b64 s[60:61], s[26:27], s[60:61]
	v_cndmask_b32_e64 v182, 0, -v9, s[60:61]
	v_add_u32_e32 v9, 0x91, v8
	v_cmp_lt_i32_e64 s[62:63], v9, v164
	v_add_u32_e32 v9, 0xb1, v8
	v_cmp_lt_i32_e64 s[64:65], v9, v164
	v_mul_f32_e64 v9, |v105|, s3
	v_exp_f32_e32 v9, v9
	v_mul_f32_e64 v11, |v89|, s3
	v_exp_f32_e32 v11, v11
	s_or_b64 s[58:59], s[26:27], s[58:59]
	v_add_f32_e32 v9, 1.0, v9
	v_log_f32_e32 v9, v9
	v_add_f32_e32 v11, 1.0, v11
	v_cndmask_b32_e64 v181, 0, -v10, s[58:59]
	v_max_f32_e32 v10, v105, v105
	v_log_f32_e32 v11, v11
	v_max_f32_e32 v10, 0, v10
	v_fmac_f32_e32 v10, 0x3f317218, v9
	v_max_f32_e32 v9, v89, v89
	v_max_f32_e32 v9, 0, v9
	v_fmac_f32_e32 v9, 0x3f317218, v11
	s_or_b64 s[64:65], s[26:27], s[64:65]
	v_cndmask_b32_e64 v184, 0, -v9, s[64:65]
	v_add_u32_e32 v9, 0x92, v8
	v_cmp_lt_i32_e64 s[66:67], v9, v164
	v_add_u32_e32 v9, 0xb2, v8
	v_cmp_lt_i32_e64 s[68:69], v9, v164
	v_mul_f32_e64 v9, |v106|, s3
	v_exp_f32_e32 v9, v9
	v_mul_f32_e64 v11, |v90|, s3
	v_exp_f32_e32 v11, v11
	s_or_b64 s[62:63], s[26:27], s[62:63]
	v_add_f32_e32 v9, 1.0, v9
	v_log_f32_e32 v9, v9
	v_add_f32_e32 v11, 1.0, v11
	v_cndmask_b32_e64 v183, 0, -v10, s[62:63]
	v_max_f32_e32 v10, v106, v106
	v_log_f32_e32 v11, v11
	v_max_f32_e32 v10, 0, v10
	v_fmac_f32_e32 v10, 0x3f317218, v9
	v_max_f32_e32 v9, v90, v90
	v_max_f32_e32 v9, 0, v9
	v_fmac_f32_e32 v9, 0x3f317218, v11
	s_or_b64 s[68:69], s[26:27], s[68:69]
	v_cndmask_b32_e64 v186, 0, -v9, s[68:69]
	v_add_u32_e32 v9, 0x93, v8
	v_cmp_lt_i32_e64 s[70:71], v9, v164
	v_add_u32_e32 v9, 0xb3, v8
	v_cmp_lt_i32_e64 s[72:73], v9, v164
	v_mul_f32_e64 v9, |v107|, s3
	v_exp_f32_e32 v9, v9
	v_mul_f32_e64 v11, |v91|, s3
	v_exp_f32_e32 v11, v11
	s_or_b64 s[66:67], s[26:27], s[66:67]
	v_add_f32_e32 v9, 1.0, v9
	v_log_f32_e32 v9, v9
	v_add_f32_e32 v11, 1.0, v11
	v_cndmask_b32_e64 v185, 0, -v10, s[66:67]
	v_max_f32_e32 v10, v107, v107
	v_log_f32_e32 v11, v11
	v_max_f32_e32 v10, 0, v10
	v_fmac_f32_e32 v10, 0x3f317218, v9
	v_max_f32_e32 v9, v91, v91
	v_max_f32_e32 v9, 0, v9
	v_fmac_f32_e32 v9, 0x3f317218, v11
	s_or_b64 s[72:73], s[26:27], s[72:73]
	v_cndmask_b32_e64 v188, 0, -v9, s[72:73]
	v_add_u32_e32 v9, 0x98, v8
	v_cmp_lt_i32_e64 s[74:75], v9, v164
	v_add_u32_e32 v9, 0xb8, v8
	v_cmp_lt_i32_e64 s[76:77], v9, v164
	v_mul_f32_e64 v9, |v108|, s3
	v_exp_f32_e32 v9, v9
	v_mul_f32_e64 v11, |v92|, s3
	v_exp_f32_e32 v11, v11
	s_or_b64 s[70:71], s[26:27], s[70:71]
	v_add_f32_e32 v9, 1.0, v9
	v_log_f32_e32 v9, v9
	v_add_f32_e32 v11, 1.0, v11
	v_cndmask_b32_e64 v187, 0, -v10, s[70:71]
	v_max_f32_e32 v10, v108, v108
	v_log_f32_e32 v11, v11
	v_max_f32_e32 v10, 0, v10
	v_fmac_f32_e32 v10, 0x3f317218, v9
	v_max_f32_e32 v9, v92, v92
	v_max_f32_e32 v9, 0, v9
	v_fmac_f32_e32 v9, 0x3f317218, v11
	s_or_b64 s[76:77], s[26:27], s[76:77]
	v_cndmask_b32_e64 v190, 0, -v9, s[76:77]
	v_add_u32_e32 v9, 0x99, v8
	v_cmp_lt_i32_e64 s[78:79], v9, v164
	v_add_u32_e32 v9, 0xb9, v8
	v_cmp_lt_i32_e64 s[80:81], v9, v164
	v_mul_f32_e64 v9, |v109|, s3
	v_exp_f32_e32 v9, v9
	v_mul_f32_e64 v11, |v93|, s3
	v_exp_f32_e32 v11, v11
	s_or_b64 s[74:75], s[26:27], s[74:75]
	v_add_f32_e32 v9, 1.0, v9
	v_log_f32_e32 v9, v9
	v_add_f32_e32 v11, 1.0, v11
	v_cndmask_b32_e64 v189, 0, -v10, s[74:75]
	v_max_f32_e32 v10, v109, v109
	v_log_f32_e32 v11, v11
	v_max_f32_e32 v10, 0, v10
	v_fmac_f32_e32 v10, 0x3f317218, v9
	v_max_f32_e32 v9, v93, v93
	v_max_f32_e32 v9, 0, v9
	v_fmac_f32_e32 v9, 0x3f317218, v11
	s_or_b64 s[80:81], s[26:27], s[80:81]
	v_cndmask_b32_e64 v192, 0, -v9, s[80:81]
	v_add_u32_e32 v9, 0x9a, v8
	v_cmp_lt_i32_e64 s[82:83], v9, v164
	v_add_u32_e32 v9, 0xba, v8
	s_mov_b32 s21, s84
	v_cmp_lt_i32_e64 s[84:85], v9, v164
	v_mul_f32_e64 v9, |v110|, s3
	v_exp_f32_e32 v9, v9
	v_mul_f32_e64 v11, |v94|, s3
	v_exp_f32_e32 v11, v11
	s_or_b64 s[78:79], s[26:27], s[78:79]
	v_add_f32_e32 v9, 1.0, v9
	v_log_f32_e32 v9, v9
	v_add_f32_e32 v11, 1.0, v11
	v_cndmask_b32_e64 v191, 0, -v10, s[78:79]
	v_max_f32_e32 v10, v110, v110
	v_log_f32_e32 v11, v11
	v_max_f32_e32 v10, 0, v10
	v_fmac_f32_e32 v10, 0x3f317218, v9
	v_max_f32_e32 v9, v94, v94
	v_max_f32_e32 v9, 0, v9
	v_fmac_f32_e32 v9, 0x3f317218, v11
	s_or_b64 s[84:85], s[26:27], s[84:85]
	v_cndmask_b32_e64 v194, 0, -v9, s[84:85]
	v_add_u32_e32 v9, 0x9b, v8
	v_add_u32_e32 v8, 0xbb, v8
	v_cmp_lt_i32_e64 s[88:89], v8, v164
	v_mul_f32_e64 v8, |v111|, s3
	s_or_b64 s[82:83], s[26:27], s[82:83]
	v_exp_f32_e32 v8, v8
	v_cndmask_b32_e64 v193, 0, -v10, s[82:83]
	v_mul_f32_e64 v10, |v95|, s3
	v_exp_f32_e32 v10, v10
	v_add_f32_e32 v8, 1.0, v8
	v_log_f32_e32 v8, v8
	s_mov_b64 s[16:17], s[86:87]
	v_add_f32_e32 v10, 1.0, v10
	v_cmp_lt_i32_e64 s[86:87], v9, v164
	v_max_f32_e32 v9, v111, v111
	v_log_f32_e32 v10, v10
	v_max_f32_e32 v9, 0, v9
	v_fmac_f32_e32 v9, 0x3f317218, v8
	v_max_f32_e32 v8, v95, v95
	v_max_f32_e32 v8, 0, v8
	v_fmac_f32_e32 v8, 0x3f317218, v10
	s_or_b64 s[86:87], s[26:27], s[86:87]
	s_or_b64 s[88:89], s[26:27], s[88:89]
	v_cndmask_b32_e64 v195, 0, -v9, s[86:87]
	v_cndmask_b32_e64 v196, 0, -v8, s[88:89]
	v_add_f32_e32 v8, v0, v2
	v_add_f32_e32 v9, v4, v6
	v_add_f32_e32 v8, v8, v9
	v_add_f32_e32 v9, v3, v5
	v_add_f32_e32 v10, v7, v15
	v_add_f32_e32 v10, v9, v10
	v_add_f32_e32 v9, v169, v176
	v_add_f32_e32 v11, v177, v179
	v_add_f32_e32 v9, v9, v11
	v_add_f32_e32 v11, v171, v173
	v_add_f32_e32 v12, v178, v180
	v_add_f32_e32 v11, v11, v12
	v_add_f32_e32 v12, v181, v183
	v_add_f32_e32 v13, v185, v187
	v_add_f32_e32 v12, v12, v13
	v_add_f32_e32 v13, v182, v184
	v_add_f32_e32 v14, v186, v188
	v_add_f32_e32 v152, v13, v14
	v_add_f32_e32 v13, v189, v191
	v_add_f32_e32 v14, v193, v195
	v_add_f32_e32 v13, v13, v14
	v_add_f32_e32 v14, v190, v192
	v_add_f32_e32 v170, v194, v196
	v_add_f32_e32 v175, v14, v170
	v_mov_b32_e32 v174, v11
	s_nop 1
	v_permlane32_swap_b32_e32 v11, v174
	v_mov_b32_e32 v204, v175
	v_add_f32_e32 v11, v11, v174
	v_cndmask_b32_e64 v202, 0, v174, s[38:39]
	v_mov_b32_e32 v174, v152
	v_permlane32_swap_b32_e32 v175, v204
	s_nop 0
	v_permlane32_swap_b32_e32 v152, v174
	v_add_f32_e32 v175, v175, v204
	v_cndmask_b32_e64 v204, 0, v204, s[38:39]
	v_cndmask_b32_e64 v203, 0, v174, s[38:39]
	v_add_f32_e32 v204, v153, v204
	v_pk_add_f32 v[152:153], v[152:153], v[174:175]
	v_mov_b32_e32 v172, v13
	v_add_f32_e32 v174, v203, v153
	v_pk_add_f32 v[152:153], v[152:153], v[152:153] op_sel:[0,1] op_sel_hi:[1,0]
	v_permlane32_swap_b32_e32 v13, v172
	v_add_f32_e32 v153, v202, v152
	v_add_f32_e32 v153, v180, v153
	v_add_f32_e32 v13, v13, v172
	v_cndmask_b32_e64 v200, 0, v172, s[38:39]
	v_mov_b32_e32 v172, v10
	v_add_f32_e32 v178, v178, v153
	s_nop 0
	v_permlane32_swap_b32_e32 v10, v172
	v_add_f32_e32 v180, v173, v178
	v_mov_b32_e32 v173, v152
	v_cndmask_b32_e64 v201, 0, v172, s[38:39]
	v_pk_add_f32 v[10:11], v[10:11], v[172:173]
	v_mov_b32_e32 v170, v9
	v_add_f32_e32 v152, v201, v11
	s_nop 0
	v_permlane32_swap_b32_e32 v9, v170
	v_add_f32_e32 v152, v15, v152
	v_add_f32_e32 v9, v9, v170
	v_cndmask_b32_e64 v198, 0, v170, s[38:39]
	v_mov_b32_e32 v170, v12
	v_add_f32_e32 v174, v188, v174
	v_add_f32_e32 v7, v7, v152
	v_pk_add_f32 v[10:11], v[10:11], v[10:11] op_sel:[0,1] op_sel_hi:[1,0]
	v_permlane32_swap_b32_e32 v12, v170
	v_add_f32_e32 v175, v186, v174
	v_add_f32_e32 v186, v171, v180
	v_add_f32_e32 v5, v5, v7
	v_add_f32_e32 v11, v200, v10
	v_mov_b32_e32 v171, v10
	v_cndmask_b32_e64 v199, 0, v170, s[38:39]
	v_add_f32_e32 v3, v3, v5
	v_add_f32_e32 v172, v195, v11
	v_pk_add_f32 v[10:11], v[12:13], v[170:171]
	v_add_f32_e32 v5, v81, v5
	v_mov_b32_e32 v14, v8
	v_add_f32_e32 v12, v199, v11
	v_pk_add_f32 v[10:11], v[10:11], v[10:11] op_sel:[0,1] op_sel_hi:[1,0]
	v_mul_f32_e32 v5, 0x3fb8aa3b, v5
	v_permlane32_swap_b32_e32 v8, v14
	v_mov_b32_e32 v15, v10
	v_exp_f32_e32 v5, v5
	v_cndmask_b32_e64 v197, 0, v14, s[38:39]
	v_pk_add_f32 v[8:9], v[8:9], v[14:15]
	v_add_f32_e32 v11, v198, v10
	v_add_f32_e32 v10, v197, v9
	v_add_f32_e32 v6, v6, v10
	v_add_f32_e32 v4, v4, v6
	v_add_f32_e32 v3, v80, v3
	v_cndmask_b32_e64 v14, 0, v5, s[4:5]
	v_add_f32_e32 v5, v99, v6
	v_add_f32_e32 v6, v83, v152
	v_mul_f32_e32 v3, 0x3fb8aa3b, v3
	v_mul_f32_e32 v6, 0x3fb8aa3b, v6
	v_exp_f32_e32 v3, v3
	v_exp_f32_e32 v6, v6
	v_add_f32_e32 v11, v179, v11
	v_add_f32_e32 v177, v177, v11
	v_add_f32_e32 v176, v176, v177
	v_add_f32_e32 v2, v2, v4
	v_cndmask_b32_e64 v10, 0, v3, s[0:1]
	v_add_f32_e32 v3, v98, v4
	v_add_f32_e32 v4, v82, v7
	v_cndmask_b32_e64 v80, 0, v6, s[12:13]
	v_add_f32_e32 v6, v84, v186
	v_add_f32_e32 v7, v101, v176
	v_mul_f32_e32 v4, 0x3fb8aa3b, v4
	v_mul_f32_e32 v5, 0x3fb8aa3b, v5
	v_mul_f32_e32 v6, 0x3fb8aa3b, v6
	v_mul_f32_e32 v7, 0x3fb8aa3b, v7
	v_exp_f32_e32 v4, v4
	v_exp_f32_e32 v5, v5
	v_exp_f32_e32 v6, v6
	v_exp_f32_e32 v7, v7
	v_add_f32_e32 v196, v196, v204
	v_add_f32_e32 v12, v187, v12
	v_add_f32_e32 v194, v194, v196
	v_add_f32_e32 v173, v193, v172
	v_add_f32_e32 v13, v185, v12
	v_add_f32_e32 v192, v192, v194
	v_add_f32_e32 v184, v184, v175
	v_add_f32_e32 v188, v191, v173
	v_add_f32_e32 v170, v183, v13
	v_add_f32_e32 v169, v169, v176
	v_add_f32_e32 v190, v190, v192
	v_add_f32_e32 v182, v182, v184
	v_add_f32_e32 v189, v189, v188
	v_add_f32_e32 v171, v181, v170
	v_add_f32_e32 v0, v0, v2
	v_add_f32_e32 v2, v97, v2
	v_cndmask_b32_e64 v15, 0, v4, s[8:9]
	v_cndmask_b32_e64 v4, 0, v5, s[10:11]
	v_add_f32_e32 v5, v100, v169
	v_add_f32_e32 v81, v85, v180
	v_cndmask_b32_e64 v82, 0, v6, s[44:45]
	v_cndmask_b32_e64 v6, 0, v7, s[46:47]
	v_add_f32_e32 v7, v102, v177
	v_add_f32_e32 v83, v86, v178
	v_add_f32_e32 v11, v103, v11
	v_add_f32_e32 v13, v106, v13
	v_add_f32_e32 v12, v107, v12
	v_add_f32_e32 v0, v96, v0
	v_mul_f32_e32 v2, 0x3fb8aa3b, v2
	v_mul_f32_e32 v3, 0x3fb8aa3b, v3
	v_mul_f32_e32 v5, 0x3fb8aa3b, v5
	v_mul_f32_e32 v81, 0x3fb8aa3b, v81
	v_mul_f32_e32 v7, 0x3fb8aa3b, v7
	v_mul_f32_e32 v83, 0x3fb8aa3b, v83
	v_mul_f32_e32 v11, 0x3fb8aa3b, v11
	v_add_f32_e32 v84, v87, v153
	v_add_f32_e32 v85, v104, v171
	v_add_f32_e32 v86, v88, v182
	v_add_f32_e32 v87, v105, v170
	v_add_f32_e32 v88, v89, v184
	v_mul_f32_e32 v13, 0x3fb8aa3b, v13
	v_add_f32_e32 v89, v90, v175
	v_mul_f32_e32 v12, 0x3fb8aa3b, v12
	v_add_f32_e32 v90, v91, v174
	v_add_f32_e32 v91, v108, v189
	v_add_f32_e32 v92, v92, v190
	v_add_f32_e32 v96, v109, v188
	v_add_f32_e32 v93, v93, v192
	v_add_f32_e32 v97, v110, v173
	v_add_f32_e32 v94, v94, v194
	v_add_f32_e32 v98, v111, v172
	v_add_f32_e32 v95, v95, v196
	v_mul_f32_e32 v0, 0x3fb8aa3b, v0
	v_exp_f32_e32 v2, v2
	v_exp_f32_e32 v3, v3
	v_exp_f32_e32 v5, v5
	v_exp_f32_e32 v81, v81
	v_exp_f32_e32 v7, v7
	v_exp_f32_e32 v83, v83
	v_exp_f32_e32 v11, v11
	v_mul_f32_e32 v84, 0x3fb8aa3b, v84
	v_mul_f32_e32 v85, 0x3fb8aa3b, v85
	v_mul_f32_e32 v86, 0x3fb8aa3b, v86
	v_mul_f32_e32 v87, 0x3fb8aa3b, v87
	v_mul_f32_e32 v88, 0x3fb8aa3b, v88
	v_exp_f32_e32 v13, v13
	v_mul_f32_e32 v89, 0x3fb8aa3b, v89
	v_exp_f32_e32 v12, v12
	v_mul_f32_e32 v90, 0x3fb8aa3b, v90
	v_mul_f32_e32 v91, 0x3fb8aa3b, v91
	v_mul_f32_e32 v92, 0x3fb8aa3b, v92
	v_mul_f32_e32 v96, 0x3fb8aa3b, v96
	v_mul_f32_e32 v93, 0x3fb8aa3b, v93
	v_mul_f32_e32 v97, 0x3fb8aa3b, v97
	v_mul_f32_e32 v94, 0x3fb8aa3b, v94
	v_mul_f32_e32 v98, 0x3fb8aa3b, v98
	v_mul_f32_e32 v95, 0x3fb8aa3b, v95
	v_exp_f32_e32 v0, v0
	v_exp_f32_e32 v84, v84
	v_exp_f32_e32 v85, v85
	v_exp_f32_e32 v86, v86
	v_exp_f32_e32 v87, v87
	v_exp_f32_e32 v88, v88
	v_exp_f32_e32 v89, v89
	v_exp_f32_e32 v90, v90
	v_exp_f32_e32 v91, v91
	v_exp_f32_e32 v92, v92
	v_exp_f32_e32 v96, v96
	v_exp_f32_e32 v93, v93
	v_exp_f32_e32 v97, v97
	v_exp_f32_e32 v94, v94
	v_exp_f32_e32 v98, v98
	v_exp_f32_e32 v95, v95
	v_cndmask_b32_e64 v2, 0, v2, s[14:15]
	v_cndmask_b32_e64 v3, 0, v3, s[6:7]
	v_cndmask_b32_e64 v5, 0, v5, s[42:43]
	v_cndmask_b32_e64 v81, 0, v81, s[48:49]
	v_cndmask_b32_e64 v7, 0, v7, s[50:51]
	v_cndmask_b32_e64 v83, 0, v83, s[52:53]
	v_cndmask_b32_e64 v11, 0, v11, s[54:55]
	v_cndmask_b32_e64 v13, 0, v13, s[66:67]
	v_cndmask_b32_e64 v12, 0, v12, s[70:71]
	v_readlane_b32 s46, v255, 18
	v_readlane_b32 s44, v255, 16
	v_readlane_b32 s52, v255, 10
	s_mov_b32 s27, s36
	s_mov_b32 s36, s35
	v_cndmask_b32_e32 v0, 0, v0, vcc
	s_mov_b32 s7, s2
	v_cndmask_b32_e64 v84, 0, v84, s[56:57]
	v_readlane_b32 s57, v255, 15
	v_readlane_b32 s56, v255, 14
	v_cndmask_b32_e64 v85, 0, v85, s[58:59]
	v_cndmask_b32_e64 v86, 0, v86, s[60:61]
	v_cndmask_b32_e64 v87, 0, v87, s[62:63]
	v_cndmask_b32_e64 v88, 0, v88, s[64:65]
	v_cndmask_b32_e64 v89, 0, v89, s[68:69]
	v_cndmask_b32_e64 v90, 0, v90, s[72:73]
	v_cndmask_b32_e64 v91, 0, v91, s[74:75]
	v_cndmask_b32_e64 v92, 0, v92, s[76:77]
	v_cndmask_b32_e64 v96, 0, v96, s[78:79]
	v_cndmask_b32_e64 v93, 0, v93, s[80:81]
	v_cndmask_b32_e64 v97, 0, v97, s[82:83]
	v_cndmask_b32_e64 v94, 0, v94, s[84:85]
	s_mov_b32 s84, s21
	v_cndmask_b32_e64 v98, 0, v98, s[86:87]
	s_mov_b64 s[86:87], s[16:17]
	v_readlane_b32 s17, v255, 39
	v_readlane_b32 s16, v255, 20
	v_readlane_b32 s47, v255, 19
	v_readlane_b32 s45, v255, 17
	v_readlane_b32 s55, v255, 13
	v_readlane_b32 s54, v255, 12
	v_readlane_b32 s53, v255, 11
	v_cndmask_b32_e64 v95, 0, v95, s[88:89]
	v_add_f32_e32 v153, v8, v9
	v_cvt_pk_bf16_f32 v2, v0, v2
	v_cvt_pk_bf16_f32 v3, v3, v4
	v_cvt_pk_bf16_f32 v4, v5, v6
	v_cvt_pk_bf16_f32 v5, v7, v11
	v_cvt_pk_bf16_f32 v6, v85, v87
	v_cvt_pk_bf16_f32 v7, v13, v12
	v_cvt_pk_bf16_f32 v8, v91, v96
	v_cvt_pk_bf16_f32 v9, v97, v98
	v_cvt_pk_bf16_f32 v10, v10, v14
	v_cvt_pk_bf16_f32 v11, v15, v80
	v_cvt_pk_bf16_f32 v12, v82, v81
	v_cvt_pk_bf16_f32 v13, v83, v84
	v_cvt_pk_bf16_f32 v80, v86, v88
	v_cvt_pk_bf16_f32 v81, v89, v90
	v_cvt_pk_bf16_f32 v82, v92, v93
	v_cvt_pk_bf16_f32 v83, v94, v95
	s_mul_i32 s0, s93, 0xa100
	v_add_u32_e32 v0, s0, v159
	s_setprio 1
	ds_read_b64_tr_b16 v[84:85], v0 offset:0x0
	ds_read_b64_tr_b16 v[86:87], v0 offset:0x100
	ds_read_b64_tr_b16 v[88:89], v0 offset:0x1000
	ds_read_b64_tr_b16 v[90:91], v0 offset:0x1100
	ds_read_b64_tr_b16 v[92:93], v0 offset:0x2000
	ds_read_b64_tr_b16 v[94:95], v0 offset:0x2100
	ds_read_b64_tr_b16 v[96:97], v0 offset:0x3000
	ds_read_b64_tr_b16 v[98:99], v0 offset:0x3100
	s_waitcnt lgkmcnt(6)
	s_nop 0
	v_mfma_f32_32x32x16_bf16 v[16:31], v[2:5], v[84:87], v[16:31]
	ds_read_b64_tr_b16 v[84:85], v0 offset:0x200
	ds_read_b64_tr_b16 v[86:87], v0 offset:0x300
	s_waitcnt lgkmcnt(6)
	v_mfma_f32_32x32x16_bf16 v[16:31], v[6:9], v[88:91], v[16:31]
	ds_read_b64_tr_b16 v[88:89], v0 offset:0x1200
	ds_read_b64_tr_b16 v[90:91], v0 offset:0x1300
	s_waitcnt lgkmcnt(6)
	v_mfma_f32_32x32x16_bf16 v[16:31], v[10:13], v[92:95], v[16:31]
	ds_read_b64_tr_b16 v[92:93], v0 offset:0x2200
	ds_read_b64_tr_b16 v[94:95], v0 offset:0x2300
	s_waitcnt lgkmcnt(6)
	v_mfma_f32_32x32x16_bf16 v[16:31], v[80:83], v[96:99], v[16:31]
	ds_read_b64_tr_b16 v[96:97], v0 offset:0x3200
	ds_read_b64_tr_b16 v[98:99], v0 offset:0x3300
	s_waitcnt lgkmcnt(6)
	v_mfma_f32_32x32x16_bf16 v[32:47], v[2:5], v[84:87], v[32:47]
	ds_read_b64_tr_b16 v[84:85], v0 offset:0x400
	ds_read_b64_tr_b16 v[86:87], v0 offset:0x500
	s_waitcnt lgkmcnt(6)
	v_mfma_f32_32x32x16_bf16 v[32:47], v[6:9], v[88:91], v[32:47]
	ds_read_b64_tr_b16 v[88:89], v0 offset:0x1400
	ds_read_b64_tr_b16 v[90:91], v0 offset:0x1500
	s_waitcnt lgkmcnt(6)
	v_mfma_f32_32x32x16_bf16 v[32:47], v[10:13], v[92:95], v[32:47]
	ds_read_b64_tr_b16 v[92:93], v0 offset:0x2400
	ds_read_b64_tr_b16 v[94:95], v0 offset:0x2500
	s_waitcnt lgkmcnt(6)
	v_mfma_f32_32x32x16_bf16 v[32:47], v[80:83], v[96:99], v[32:47]
	ds_read_b64_tr_b16 v[96:97], v0 offset:0x3400
	ds_read_b64_tr_b16 v[98:99], v0 offset:0x3500
	s_waitcnt lgkmcnt(6)
	v_mfma_f32_32x32x16_bf16 v[48:63], v[2:5], v[84:87], v[48:63]
	ds_read_b64_tr_b16 v[84:85], v0 offset:0x600
	ds_read_b64_tr_b16 v[86:87], v0 offset:0x700
	s_waitcnt lgkmcnt(6)
	v_mfma_f32_32x32x16_bf16 v[48:63], v[6:9], v[88:91], v[48:63]
	ds_read_b64_tr_b16 v[88:89], v0 offset:0x1600
	ds_read_b64_tr_b16 v[90:91], v0 offset:0x1700
	s_waitcnt lgkmcnt(6)
	v_mfma_f32_32x32x16_bf16 v[48:63], v[10:13], v[92:95], v[48:63]
	ds_read_b64_tr_b16 v[92:93], v0 offset:0x2600
	ds_read_b64_tr_b16 v[94:95], v0 offset:0x2700
	s_waitcnt lgkmcnt(6)
	v_mfma_f32_32x32x16_bf16 v[48:63], v[80:83], v[96:99], v[48:63]
	ds_read_b64_tr_b16 v[96:97], v0 offset:0x3600
	ds_read_b64_tr_b16 v[98:99], v0 offset:0x3700
	s_waitcnt lgkmcnt(6)
	v_mfma_f32_32x32x16_bf16 v[64:79], v[2:5], v[84:87], v[64:79]
	s_waitcnt lgkmcnt(4)
	v_mfma_f32_32x32x16_bf16 v[64:79], v[6:9], v[88:91], v[64:79]
	s_waitcnt lgkmcnt(2)
	v_mfma_f32_32x32x16_bf16 v[64:79], v[10:13], v[92:95], v[64:79]
	s_waitcnt lgkmcnt(0)
	v_mfma_f32_32x32x16_bf16 v[64:79], v[80:83], v[96:99], v[64:79]
	s_setprio 0

.LBB0_1281:
	v_add_f32_e32 v121, v2, v3
	v_fmac_f32_e32 v121, v96, v108
	v_cvt_pk_bf16_f32 v2, v109, v112
	v_cvt_pk_bf16_f32 v3, v113, v114
	v_cvt_pk_bf16_f32 v4, v115, v110
	v_cvt_pk_bf16_f32 v5, v116, v117
	v_cvt_pk_bf16_f32 v106, v111, v106
	v_cvt_pk_bf16_f32 v107, v107, v102
	v_cvt_pk_bf16_f32 v108, v103, v118
	v_cvt_pk_bf16_f32 v109, v119, v120
	v_cvt_pk_bf16_f32 v98, v98, v99
	v_cvt_pk_bf16_f32 v99, v100, v101
	v_cvt_pk_bf16_f32 v100, v14, v15
	v_cvt_pk_bf16_f32 v101, v104, v105
	v_cvt_pk_bf16_f32 v6, v6, v7
	v_cvt_pk_bf16_f32 v7, v8, v9
	v_cvt_pk_bf16_f32 v8, v12, v13
	v_cvt_pk_bf16_f32 v9, v10, v11
	s_nop 0
	v_add_u32_e32 v14, s2, v186
	s_setprio 1
	ds_read_b64_tr_b16 v[10:11], v14 offset:0x0
	ds_read_b64_tr_b16 v[12:13], v14 offset:0x100
	ds_read_b64_tr_b16 v[102:103], v14 offset:0x1000
	ds_read_b64_tr_b16 v[104:105], v14 offset:0x1100
	ds_read_b64_tr_b16 v[110:111], v14 offset:0x2000
	ds_read_b64_tr_b16 v[112:113], v14 offset:0x2100
	ds_read_b64_tr_b16 v[114:115], v14 offset:0x3000
	ds_read_b64_tr_b16 v[116:117], v14 offset:0x3100
	s_waitcnt lgkmcnt(6)
	s_nop 0
	v_mfma_f32_32x32x16_bf16 v[64:79], v[2:5], v[10:13], v[64:79]
	ds_read_b64_tr_b16 v[10:11], v14 offset:0x200
	ds_read_b64_tr_b16 v[12:13], v14 offset:0x300
	s_waitcnt lgkmcnt(6)
	v_mfma_f32_32x32x16_bf16 v[64:79], v[106:109], v[102:105], v[64:79]
	ds_read_b64_tr_b16 v[102:103], v14 offset:0x1200
	ds_read_b64_tr_b16 v[104:105], v14 offset:0x1300
	s_waitcnt lgkmcnt(6)
	v_mfma_f32_32x32x16_bf16 v[64:79], v[98:101], v[110:113], v[64:79]
	ds_read_b64_tr_b16 v[110:111], v14 offset:0x2200
	ds_read_b64_tr_b16 v[112:113], v14 offset:0x2300
	s_waitcnt lgkmcnt(6)
	v_mfma_f32_32x32x16_bf16 v[64:79], v[6:9], v[114:117], v[64:79]
	ds_read_b64_tr_b16 v[114:115], v14 offset:0x3200
	ds_read_b64_tr_b16 v[116:117], v14 offset:0x3300
	s_waitcnt lgkmcnt(6)
	v_mfma_f32_32x32x16_bf16 v[48:63], v[2:5], v[10:13], v[48:63]
	ds_read_b64_tr_b16 v[10:11], v14 offset:0x400
	ds_read_b64_tr_b16 v[12:13], v14 offset:0x500
	s_waitcnt lgkmcnt(6)
	v_mfma_f32_32x32x16_bf16 v[48:63], v[106:109], v[102:105], v[48:63]
	ds_read_b64_tr_b16 v[102:103], v14 offset:0x1400
	ds_read_b64_tr_b16 v[104:105], v14 offset:0x1500
	s_waitcnt lgkmcnt(6)
	v_mfma_f32_32x32x16_bf16 v[48:63], v[98:101], v[110:113], v[48:63]
	ds_read_b64_tr_b16 v[110:111], v14 offset:0x2400
	ds_read_b64_tr_b16 v[112:113], v14 offset:0x2500
	s_waitcnt lgkmcnt(6)
	v_mfma_f32_32x32x16_bf16 v[48:63], v[6:9], v[114:117], v[48:63]
	ds_read_b64_tr_b16 v[114:115], v14 offset:0x3400
	ds_read_b64_tr_b16 v[116:117], v14 offset:0x3500
	s_waitcnt lgkmcnt(6)
	v_mfma_f32_32x32x16_bf16 v[32:47], v[2:5], v[10:13], v[32:47]
	ds_read_b64_tr_b16 v[10:11], v14 offset:0x600
	ds_read_b64_tr_b16 v[12:13], v14 offset:0x700
	s_waitcnt lgkmcnt(6)
	v_mfma_f32_32x32x16_bf16 v[32:47], v[106:109], v[102:105], v[32:47]
	ds_read_b64_tr_b16 v[102:103], v14 offset:0x1600
	ds_read_b64_tr_b16 v[104:105], v14 offset:0x1700
	s_waitcnt lgkmcnt(6)
	v_mfma_f32_32x32x16_bf16 v[32:47], v[98:101], v[110:113], v[32:47]
	ds_read_b64_tr_b16 v[110:111], v14 offset:0x2600
	ds_read_b64_tr_b16 v[112:113], v14 offset:0x2700
	s_waitcnt lgkmcnt(6)
	v_mfma_f32_32x32x16_bf16 v[32:47], v[6:9], v[114:117], v[32:47]
	ds_read_b64_tr_b16 v[114:115], v14 offset:0x3600
	ds_read_b64_tr_b16 v[116:117], v14 offset:0x3700
	s_waitcnt lgkmcnt(6)
	v_mfma_f32_32x32x16_bf16 v[16:31], v[2:5], v[10:13], v[16:31]
	s_waitcnt lgkmcnt(4)
	v_mfma_f32_32x32x16_bf16 v[16:31], v[106:109], v[102:105], v[16:31]
	s_waitcnt lgkmcnt(2)
	v_mfma_f32_32x32x16_bf16 v[16:31], v[98:101], v[110:113], v[16:31]
	s_waitcnt lgkmcnt(0)
	v_mfma_f32_32x32x16_bf16 v[16:31], v[6:9], v[114:117], v[16:31]
	s_setprio 0
	v_mov_b32_e32 v96, v121
